# attention: importance rows rotated by query index in LDS so the per-tile ds_add_f32 atomics are bank-conflict free (was 32-way); block-selection reads use the same rotation
# speedup vs baseline: 1.0055x; 1.0055x over previous
; template <int BR>
; DI void attn_branch(const AttnCtx& c, unsigned long long tmask, const bf16_t* kbase, size_t kpitch, const bf16_t* vbase, size_t vpitch, f32x16 (&o)[2], float& lsum) {
;     ...
;                 f32x16 s0, s1;
; #pragma unroll
;                 for (int i = 0; i < 16; ++i) { s0[i] = sbias; s1[i] = sbias; }
; #pragma unroll
;                 for (int st = 0; st < 4; ++st) {
;                     const bf16x8 kf0 = *(const LAS bf16x8*)(Ks + c.qi * 72 + 16 * st + 8 * c.hi), kf1 = *(const LAS bf16x8*)(Ks + (32 + c.qi) * 72 + 16 * st + 8 * c.hi);
;                     s0 = MFMA32(kf0, c.q[st], s0); s1 = MFMA32(kf1, c.q[st], s1);
;                 }
;                 float p0[16], p1[16];
; #pragma unroll
;                 for (int i = 0; i < 16; ++i) { p0[i] = __builtin_amdgcn_exp2f(s0[i]); p1[i] = __builtin_amdgcn_exp2f(s1[i]); }
;                 {
;                     float l0 = 0.f, l1 = 0.f;
; #pragma unroll
;                     for (int i = 0; i < 16; ++i) { l0 += p0[i]; l1 += p1[i]; }
;                     lsum += l0 + l1;
;                 }
;                 if (BR == 1) {
; #pragma unroll
;                     for (int gq = 0; gq < 4; ++gq) {
;                         const int jj = jc * 16 + gq * 2 + c.hi;
;                         __hip_atomic_fetch_add(c.impw + jj, (p0[4 * gq] + p0[4 * gq + 1]) + (p0[4 * gq + 2] + p0[4 * gq + 3]), __ATOMIC_RELAXED, __HIP_MEMORY_SCOPE_WORKGROUP);
;                         __hip_atomic_fetch_add(c.impw + jj + 1, p0[4 * gq + 3], __ATOMIC_RELAXED, __HIP_MEMORY_SCOPE_WORKGROUP);
;                     }
; #pragma unroll
;                     for (int gq = 0; gq < 4; ++gq) {
;                         const int jj = jc * 16 + 8 + gq * 2 + c.hi;
;                         __hip_atomic_fetch_add(c.impw + jj, (p1[4 * gq] + p1[4 * gq + 1]) + (p1[4 * gq + 2] + p1[4 * gq + 3]), __ATOMIC_RELAXED, __HIP_MEMORY_SCOPE_WORKGROUP);
;                         if (jj + 1 < 64) __hip_atomic_fetch_add(c.impw + jj + 1, p1[4 * gq + 3], __ATOMIC_RELAXED, __HIP_MEMORY_SCOPE_WORKGROUP);
;                     }
;                 }
;                 if (BR != 0) {
;                     unsigned pa[8], pb[8];
; #pragma unroll
;                     for (int i = 0; i < 8; ++i) { pa[i] = pk2(p0[2 * i], p0[2 * i + 1]); pb[i] = pk2(p1[2 * i], p1[2 * i + 1]); }
; #pragma unroll
;                     for (int f = 0; f < 2; ++f) {
.LBB0_326:
	v_lshlrev_b32_e32 v32, 1, v170
	v_add3_u32 v98, s15, v185, v32
	ds_read_b128 v[32:35], v98
	ds_read_b128 v[94:97], v98 offset:32
	s_lshl_b32 s13, s12, 4
	s_waitcnt lgkmcnt(1)
	v_mfma_f32_32x32x16_bf16 v[48:63], v[32:35], v[130:133], 0
	ds_read_b128 v[32:35], v98 offset:4608
	s_waitcnt lgkmcnt(1)
	v_mfma_f32_32x32x16_bf16 v[48:63], v[94:97], v[134:137], v[48:63]
	ds_read_b128 v[94:97], v98 offset:4640
	s_waitcnt lgkmcnt(1)
	v_mfma_f32_32x32x16_bf16 v[32:47], v[32:35], v[130:133], 0
	s_waitcnt lgkmcnt(0)
	v_mfma_f32_32x32x16_bf16 v[32:47], v[94:97], v[134:137], v[32:47]
	ds_read_b128 v[94:97], v98 offset:64
	s_waitcnt lgkmcnt(0)
	v_mfma_f32_32x32x16_bf16 v[48:63], v[94:97], v[138:141], v[48:63]
	ds_read_b128 v[94:97], v98 offset:4672
	s_waitcnt lgkmcnt(0)
	v_mfma_f32_32x32x16_bf16 v[32:47], v[94:97], v[138:141], v[32:47]
	ds_read_b128 v[94:97], v98 offset:96
	s_waitcnt lgkmcnt(0)
	v_mfma_f32_32x32x16_bf16 v[48:63], v[94:97], v[142:145], v[48:63]
	ds_read_b128 v[94:97], v98 offset:4704
	s_waitcnt lgkmcnt(0)
	v_mfma_f32_32x32x16_bf16 v[32:47], v[94:97], v[142:145], v[32:47]
	s_nop 8
	v_exp_f32_e32 v102, v48
	v_exp_f32_e32 v103, v49
	v_exp_f32_e32 v101, v50
	v_exp_f32_e32 v96, v51
	v_exp_f32_e32 v98, v52
	v_exp_f32_e32 v94, v53
	v_exp_f32_e32 v53, v54
	v_exp_f32_e32 v52, v55
	v_exp_f32_e32 v50, v56
	v_exp_f32_e32 v51, v57
	v_exp_f32_e32 v49, v58
	v_exp_f32_e32 v48, v59
	v_add_f32_e32 v54, v102, v103
	v_add_f32_e32 v55, v101, v96
	v_lshl_add_u32 v59, s12, 6, v92
	v_add_f32_e32 v54, v54, v55
	v_exp_f32_e32 v99, v32
	v_exp_f32_e32 v100, v33
	v_exp_f32_e32 v95, v34
	v_exp_f32_e32 v97, v35
	v_exp_f32_e32 v35, v60
	v_exp_f32_e32 v34, v61
	v_exp_f32_e32 v33, v62
	v_exp_f32_e32 v32, v63
	v_mov_b32_e32 v254, 0xff
	v_bfe_u32 v252, v59, 8, 6
	v_lshl_add_u32 v252, v252, 2, v59
	v_bfi_b32 v253, v254, v252, v59
	ds_add_f32 v253, v54
	v_add_u32_e32 v253, 4, v252
	v_bfi_b32 v253, v254, v253, v59
	ds_add_f32 v253, v96
	v_add_f32_e32 v54, v98, v94
	v_add_f32_e32 v55, v53, v52
	v_add_f32_e32 v54, v54, v55
	v_add_u32_e32 v253, 8, v252
	v_bfi_b32 v253, v254, v253, v59
	ds_add_f32 v253, v54
	v_add_u32_e32 v253, 12, v252
	v_bfi_b32 v253, v254, v253, v59
	ds_add_f32 v253, v52
	v_add_f32_e32 v54, v50, v51
	v_add_f32_e32 v55, v49, v48
	v_add_f32_e32 v54, v54, v55
	v_add_u32_e32 v253, 16, v252
	v_bfi_b32 v253, v254, v253, v59
	ds_add_f32 v253, v54
	v_add_u32_e32 v253, 20, v252
	v_bfi_b32 v253, v254, v253, v59
	ds_add_f32 v253, v48
	v_add_f32_e32 v54, v35, v34
	v_add_f32_e32 v55, v33, v32
	v_add_f32_e32 v54, v54, v55
	v_add_u32_e32 v253, 24, v252
	v_bfi_b32 v253, v254, v253, v59
	ds_add_f32 v253, v54
	v_add_u32_e32 v253, 28, v252
	v_bfi_b32 v253, v254, v253, v59
	ds_add_f32 v253, v32
	v_add_f32_e32 v54, v99, v100
	v_add_f32_e32 v55, v95, v97
	v_add_f32_e32 v54, v54, v55
	v_add_u32_e32 v253, 32, v252
	v_bfi_b32 v253, v254, v253, v59
	ds_add_f32 v253, v54
	v_or_b32_e32 v54, s13, v87
	v_cmp_gt_u32_e32 vcc, 63, v54
	s_and_saveexec_b64 s[10:11], vcc
	v_mov_b32_e32 v254, 0xff
	v_bfe_u32 v252, v59, 8, 6
	v_lshl_add_u32 v252, v252, 2, v59
	v_add_u32_e32 v253, 36, v252
	v_bfi_b32 v253, v254, v253, v59
	ds_add_f32 v253, v97
	s_or_b64 exec, exec, s[10:11]
	v_exp_f32_e32 v58, v36
	v_exp_f32_e32 v57, v37
	v_exp_f32_e32 v56, v38
	v_exp_f32_e32 v55, v39
	v_add_f32_e32 v36, v58, v57
	v_add_f32_e32 v37, v56, v55
	v_add_f32_e32 v36, v36, v37
	v_mov_b32_e32 v254, 0xff
	v_bfe_u32 v252, v59, 8, 6
	v_lshl_add_u32 v252, v252, 2, v59
	v_add_u32_e32 v253, 40, v252
	v_bfi_b32 v253, v254, v253, v59
	ds_add_f32 v253, v36
	v_or_b32_e32 v36, s13, v88
	v_cmp_gt_u32_e32 vcc, 63, v36
	s_and_saveexec_b64 s[10:11], vcc
	v_mov_b32_e32 v254, 0xff
	v_bfe_u32 v252, v59, 8, 6
	v_lshl_add_u32 v252, v252, 2, v59
	v_add_u32_e32 v253, 44, v252
	v_bfi_b32 v253, v254, v253, v59
	ds_add_f32 v253, v55
	s_or_b64 exec, exec, s[10:11]
	v_exp_f32_e32 v54, v40
	v_exp_f32_e32 v41, v41
	v_exp_f32_e32 v40, v42
	v_exp_f32_e32 v39, v43
	v_add_f32_e32 v36, v54, v41
	v_add_f32_e32 v37, v40, v39
	v_add_f32_e32 v36, v36, v37
	v_mov_b32_e32 v254, 0xff
	v_bfe_u32 v252, v59, 8, 6
	v_lshl_add_u32 v252, v252, 2, v59
	v_add_u32_e32 v253, 48, v252
	v_bfi_b32 v253, v254, v253, v59
	ds_add_f32 v253, v36
	v_or_b32_e32 v36, s13, v89
	v_cmp_gt_u32_e32 vcc, 63, v36
	s_and_saveexec_b64 s[10:11], vcc
	v_mov_b32_e32 v254, 0xff
	v_bfe_u32 v252, v59, 8, 6
	v_lshl_add_u32 v252, v252, 2, v59
	v_add_u32_e32 v253, 52, v252
	v_bfi_b32 v253, v254, v253, v59
	ds_add_f32 v253, v39
	s_or_b64 exec, exec, s[10:11]
	v_exp_f32_e32 v42, v44
	v_exp_f32_e32 v38, v45
	v_exp_f32_e32 v37, v46
	v_exp_f32_e32 v36, v47
	v_add_f32_e32 v43, v42, v38
	v_add_f32_e32 v44, v37, v36
	v_add_f32_e32 v43, v43, v44
	v_mov_b32_e32 v254, 0xff
	v_bfe_u32 v252, v59, 8, 6
	v_lshl_add_u32 v252, v252, 2, v59
	v_add_u32_e32 v253, 56, v252
	v_bfi_b32 v253, v254, v253, v59
	ds_add_f32 v253, v43
	v_or_b32_e32 v43, s13, v90
	v_cmp_gt_u32_e32 vcc, 63, v43
	s_and_saveexec_b64 s[10:11], vcc
	v_mov_b32_e32 v254, 0xff
	v_bfe_u32 v252, v59, 8, 6
	v_lshl_add_u32 v252, v252, 2, v59
	v_add_u32_e32 v253, 60, v252
	v_bfi_b32 v253, v254, v253, v59
	ds_add_f32 v253, v36
	s_or_b64 exec, exec, s[10:11]
	v_add3_u32 v59, s15, v186, v170
	v_add_u32_e32 v110, 0x2000, v59
	ds_read2_b64 v[44:47], v110 offset0:128 offset1:130
	v_add_f32_e32 v60, 0, v99
	v_add_f32_e32 v43, 0, v102
	v_add_f32_e32 v111, v100, v60
	v_cvt_pk_bf16_f32 v60, v102, v103
	v_cvt_pk_bf16_f32 v61, v101, v96
	v_cvt_pk_bf16_f32 v62, v98, v94
	v_cvt_pk_bf16_f32 v63, v53, v52
	v_add_f32_e32 v43, v103, v43
	v_add_f32_e32 v43, v101, v43
	s_waitcnt lgkmcnt(0)
; #define LAS __attribute__((address_space(3)))
; template <int BR>
; DI void attn_branch(const AttnCtx& c, unsigned long long tmask, const bf16_t* kbase, size_t kpitch, const bf16_t* vbase, size_t vpitch, f32x16 (&o)[2], float& lsum) {
;     ...
;                 if (BR != 0) {
;                     unsigned pa[8], pb[8];
; #pragma unroll
;                     for (int i = 0; i < 8; ++i) { pa[i] = pk2(p0[2 * i], p0[2 * i + 1]); pb[i] = pk2(p1[2 * i], p1[2 * i + 1]); }
; #pragma unroll
;                     for (int f = 0; f < 2; ++f) {
;                         const u32x4 bw0 = {pa[4 * f], pa[4 * f + 1], pa[4 * f + 2], pa[4 * f + 3]}, bw1 = {pb[4 * f], pb[4 * f + 1], pb[4 * f + 2], pb[4 * f + 3]};
; #pragma unroll
;                         for (int mt = 0; mt < 2; ++mt) {
;                             const LAS bf16_t* vp = Vs + (mt * 32 + c.qi) * 68 + f * 16 + 4 * c.hi;
;                             const u32x2 a0 = *(const LAS u32x2*)vp, a1 = *(const LAS u32x2*)(vp + 8), a2 = *(const LAS u32x2*)(vp + 32), a3 = *(const LAS u32x2*)(vp + 40);
;                             const u32x4 aw0 = {a0.x, a0.y, a1.x, a1.y}, aw1 = {a2.x, a2.y, a3.x, a3.y};
;                             o[mt] = MFMA32(__builtin_bit_cast(bf16x8, aw0), __builtin_bit_cast(bf16x8, bw0), o[mt]);
;                             o[mt] = MFMA32(__builtin_bit_cast(bf16x8, aw1), __builtin_bit_cast(bf16x8, bw1), o[mt]);
;                         }
;                     }
;     ...
;             for (int sub = 0; sub < 2; ++sub) {
;                 const int key0 = jc * 64 + sub * 32;
;                 bool skip;
;                 if (BR <= 1) skip = key0 >= c.ncvw;
;                 else if (BR == 2) skip = key0 > c.tw + 31;
;                 else skip = (key0 + 31 < c.tw - 511) || (key0 > c.tw + 31);
;                 if (skip) continue;
;                 f32x16 s;
; #pragma unroll
;                 for (int i = 0; i < 16; ++i) s[i] = sbias;
; #pragma unroll
;                 for (int st = 0; st < 4; ++st) { const bf16x8 kf = *(const LAS bf16x8*)(Ks + (sub * 32 + c.qi) * 72 + 16 * st + 8 * c.hi); s = MFMA32(kf, c.q[st], s); }
;                 float p[16];
; #pragma unroll
;                 for (int i = 0; i < 16; ++i) p[i] = __builtin_amdgcn_exp2f(s[i]);
;                 int lim;
;                 if (BR <= 1) lim = c.ncv - 1 - key0 - 4 * c.hi; else lim = c.t - key0 - 4 * c.hi;
; #pragma unroll
	v_mfma_f32_32x32x16_bf16 v[16:31], v[44:47], v[60:63], v[16:31]
	v_cvt_pk_bf16_f32 v44, v99, v100
	v_add_u32_e32 v99, 0x3000, v59
	ds_read2_b64 v[100:103], v99 offset0:160 offset1:162
	ds_read2_b64 v[106:109], v110 offset0:136 offset1:138
	v_add_f32_e32 v59, v95, v111
	v_add_f32_e32 v43, v96, v43
	v_add_f32_e32 v59, v97, v59
	v_cvt_pk_bf16_f32 v46, v58, v57
	v_add_f32_e32 v43, v98, v43
	v_add_f32_e32 v58, v58, v59
	v_cvt_pk_bf16_f32 v45, v95, v97
	v_add_f32_e32 v43, v94, v43
	ds_read2_b64 v[94:97], v99 offset0:168 offset1:170
	v_add_f32_e32 v57, v57, v58
	v_cvt_pk_bf16_f32 v47, v56, v55
	s_waitcnt lgkmcnt(2)
	v_mfma_f32_32x32x16_bf16 v[0:15], v[100:103], v[60:63], v[0:15]
	v_add_f32_e32 v43, v53, v43
	v_add_f32_e32 v53, v56, v57
	ds_read2_b64 v[56:59], v110 offset0:132 offset1:134
	v_add_f32_e32 v43, v52, v43
	v_add_f32_e32 v52, v55, v53
	v_add_f32_e32 v43, v50, v43
	v_add_f32_e32 v55, v54, v52
	s_waitcnt lgkmcnt(2)
	v_mfma_f32_32x32x16_bf16 v[16:31], v[106:109], v[44:47], v[16:31]
	v_add_f32_e32 v43, v51, v43
	v_add_f32_e32 v62, v41, v55
	v_add_f32_e32 v43, v49, v43
	v_cvt_pk_bf16_f32 v55, v40, v39
	v_add_f32_e32 v40, v40, v62
	v_cvt_pk_bf16_f32 v54, v54, v41
	v_add_f32_e32 v41, v48, v43
	s_waitcnt lgkmcnt(1)
	v_mfma_f32_32x32x16_bf16 v[0:15], v[94:97], v[44:47], v[0:15]
	v_cvt_pk_bf16_f32 v44, v50, v51
	v_cvt_pk_bf16_f32 v45, v49, v48
	v_cvt_pk_bf16_f32 v46, v35, v34
	v_cvt_pk_bf16_f32 v47, v33, v32
	v_add_f32_e32 v39, v39, v40
	ds_read2_b64 v[50:53], v110 offset0:140 offset1:142
	v_add_f32_e32 v35, v35, v41
	s_waitcnt lgkmcnt(1)
	v_mfma_f32_32x32x16_bf16 v[16:31], v[56:59], v[44:47], v[16:31]
	ds_read2_b64 v[58:61], v99 offset0:164 offset1:166
	v_cvt_pk_bf16_f32 v56, v42, v38
	v_add_f32_e32 v39, v42, v39
	ds_read2_b64 v[40:43], v99 offset0:172 offset1:174
	v_cvt_pk_bf16_f32 v57, v37, v36
	v_add_f32_e32 v34, v34, v35
	v_add_f32_e32 v35, v38, v39
	s_waitcnt lgkmcnt(1)
	v_mfma_f32_32x32x16_bf16 v[0:15], v[58:61], v[44:47], v[0:15]
	v_add_f32_e32 v33, v33, v34
	v_add_f32_e32 v34, v37, v35
	v_add_f32_e32 v32, v32, v33
	v_add_f32_e32 v33, v36, v34
	v_add_f32_e32 v32, v32, v33
	v_add_f32_e32 v93, v93, v32
	v_mfma_f32_32x32x16_bf16 v[16:31], v[50:53], v[54:57], v[16:31]
	s_waitcnt lgkmcnt(0)
	v_mfma_f32_32x32x16_bf16 v[0:15], v[40:43], v[54:57], v[0:15]
	s_andn2_saveexec_b64 s[8:9], s[8:9]
	s_cbranch_execz .LBB0_325
.LBB0_335:
	s_lshl_b32 s17, s12, 4
	v_cmp_le_i32_e32 vcc, s16, v84
	s_and_saveexec_b64 s[10:11], vcc
	s_cbranch_execz .LBB0_345
	v_add3_u32 v52, s15, v185, v128
	ds_read_b128 v[32:35], v52
	ds_read_b128 v[48:51], v52 offset:32
	s_not_b32 s12, s16
	v_or_b32_e32 v53, s17, v78
	s_waitcnt lgkmcnt(1)
	v_mfma_f32_32x32x16_bf16 v[32:47], v[32:35], v[130:133], 0
	s_waitcnt lgkmcnt(0)
	v_mfma_f32_32x32x16_bf16 v[32:47], v[48:51], v[134:137], v[32:47]
	ds_read_b128 v[48:51], v52 offset:64
	ds_read_b128 v[56:59], v52 offset:96
	v_lshl_add_u32 v52, v53, 2, v86
	s_waitcnt lgkmcnt(1)
	v_mfma_f32_32x32x16_bf16 v[32:47], v[48:51], v[138:141], v[32:47]
	v_sub_u32_e32 v48, s12, v91
	v_add_u32_e32 v54, v48, v73
	v_cmp_lt_i32_e32 vcc, -1, v54
	s_waitcnt lgkmcnt(0)
	v_mfma_f32_32x32x16_bf16 v[32:47], v[56:59], v[142:145], v[32:47]
	s_nop 11
	v_exp_f32_e32 v32, v32
	v_exp_f32_e32 v33, v33
	v_exp_f32_e32 v34, v34
	v_exp_f32_e32 v35, v35
	v_cndmask_b32_e32 v48, 0, v32, vcc
	v_cmp_lt_i32_e32 vcc, 0, v54
	s_nop 1
	v_cndmask_b32_e32 v32, 0, v33, vcc
	v_cmp_lt_i32_e32 vcc, 1, v54
	s_nop 1
	v_cndmask_b32_e32 v33, 0, v34, vcc
	v_cmp_lt_i32_e32 vcc, 2, v54
	v_add_f32_e32 v34, v48, v32
	s_nop 0
	v_cndmask_b32_e32 v35, 0, v35, vcc
	v_add_f32_e32 v49, v33, v35
	v_add_f32_e32 v34, v34, v49
	v_mov_b32_e32 v254, 0xff
	v_bfe_u32 v252, v52, 8, 6
	v_lshl_add_u32 v252, v252, 2, v52
	v_bfi_b32 v253, v254, v252, v52
	ds_add_f32 v253, v34
	v_cmp_gt_u32_e32 vcc, 63, v53
	s_and_saveexec_b64 s[12:13], vcc
	v_mov_b32_e32 v254, 0xff
	v_bfe_u32 v252, v52, 8, 6
	v_lshl_add_u32 v252, v252, 2, v52
	v_add_u32_e32 v253, 4, v252
	v_bfi_b32 v253, v254, v253, v52
	ds_add_f32 v253, v35
	s_or_b64 exec, exec, s[12:13]
	v_exp_f32_e32 v34, v36
	v_exp_f32_e32 v36, v37
	v_exp_f32_e32 v37, v38
	v_exp_f32_e32 v38, v39
	v_cmp_lt_i32_e32 vcc, 7, v54
	s_nop 1
	v_cndmask_b32_e32 v49, 0, v34, vcc
	v_cmp_lt_i32_e32 vcc, 8, v54
	s_nop 1
	v_cndmask_b32_e32 v50, 0, v36, vcc
	v_cmp_lt_i32_e32 vcc, 9, v54
	v_add_f32_e32 v36, v49, v50
	s_nop 0
	v_cndmask_b32_e32 v51, 0, v37, vcc
	v_cmp_lt_i32_e32 vcc, 10, v54
	s_nop 1
	v_cndmask_b32_e32 v34, 0, v38, vcc
	v_add_f32_e32 v37, v51, v34
	v_add_f32_e32 v36, v36, v37
	v_mov_b32_e32 v254, 0xff
	v_bfe_u32 v252, v52, 8, 6
	v_lshl_add_u32 v252, v252, 2, v52
	v_add_u32_e32 v253, 8, v252
	v_bfi_b32 v253, v254, v253, v52
	ds_add_f32 v253, v36
	v_or_b32_e32 v36, 2, v53
	v_cmp_gt_u32_e32 vcc, 63, v36
	s_and_saveexec_b64 s[12:13], vcc
	v_mov_b32_e32 v254, 0xff
	v_bfe_u32 v252, v52, 8, 6
	v_lshl_add_u32 v252, v252, 2, v52
	v_add_u32_e32 v253, 12, v252
	v_bfi_b32 v253, v254, v253, v52
	ds_add_f32 v253, v34
	s_or_b64 exec, exec, s[12:13]
	v_exp_f32_e32 v36, v40
	v_exp_f32_e32 v37, v41
	v_exp_f32_e32 v38, v42
	v_exp_f32_e32 v40, v43
	v_cmp_lt_i32_e32 vcc, 15, v54
	s_nop 1
	v_cndmask_b32_e32 v39, 0, v36, vcc
	v_cmp_lt_i32_e32 vcc, 16, v54
	s_nop 1
	v_cndmask_b32_e32 v36, 0, v37, vcc
	v_cmp_lt_i32_e32 vcc, 17, v54
	s_nop 1
	v_cndmask_b32_e32 v37, 0, v38, vcc
	v_cmp_lt_i32_e32 vcc, 18, v54
	s_nop 1
	v_cndmask_b32_e32 v38, 0, v40, vcc
	v_add_f32_e32 v40, v39, v36
	v_add_f32_e32 v41, v37, v38
	v_add_f32_e32 v40, v40, v41
	v_mov_b32_e32 v254, 0xff
	v_bfe_u32 v252, v52, 8, 6
	v_lshl_add_u32 v252, v252, 2, v52
	v_add_u32_e32 v253, 16, v252
	v_bfi_b32 v253, v254, v253, v52
; #define LAS __attribute__((address_space(3)))
; DI unsigned pk2(float a, float b) { f32x2 v = {a, b}; bf2_t r = __builtin_convertvector(v, bf2_t); return __builtin_bit_cast(unsigned, r); }
; #define MFMA32(a, b, c) __builtin_amdgcn_mfma_f32_32x32x16_bf16((a), (b), (c), 0, 0, 0)
; template <int BR>
; DI void attn_branch(const AttnCtx& c, unsigned long long tmask, const bf16_t* kbase, size_t kpitch, const bf16_t* vbase, size_t vpitch, f32x16 (&o)[2], float& lsum) {
;     ...
;                 if (BR == 1) {
; #pragma unroll
;                     for (int gq = 0; gq < 4; ++gq) {
;                         const int jj = jc * 16 + sub * 8 + gq * 2 + c.hi;
;                         __hip_atomic_fetch_add(c.impw + jj, (p[4 * gq] + p[4 * gq + 1]) + (p[4 * gq + 2] + p[4 * gq + 3]), __ATOMIC_RELAXED, __HIP_MEMORY_SCOPE_WORKGROUP);
;                         if (jj + 1 < 64) __hip_atomic_fetch_add(c.impw + jj + 1, p[4 * gq + 3], __ATOMIC_RELAXED, __HIP_MEMORY_SCOPE_WORKGROUP);
;                     }
;                 }
;                 unsigned pp[8];
; #pragma unroll
;                 for (int i = 0; i < 8; ++i) pp[i] = pk2(p[2 * i], p[2 * i + 1]);
; #pragma unroll
;                 for (int f = 0; f < 2; ++f) {
;                     const u32x4 bw = {pp[4 * f], pp[4 * f + 1], pp[4 * f + 2], pp[4 * f + 3]};
;                     const bf16x8 bfr = __builtin_bit_cast(bf16x8, bw);
; #pragma unroll
;                     for (int mt = 0; mt < 2; ++mt) {
;                         const LAS bf16_t* vp = Vs + (mt * 32 + c.qi) * 68 + sub * 32 + f * 16 + 4 * c.hi;
;                         const u32x2 a0 = *(const LAS u32x2*)vp, a1 = *(const LAS u32x2*)(vp + 8);
;                         const u32x4 aw = {a0.x, a0.y, a1.x, a1.y};
;                         o[mt] = MFMA32(__builtin_bit_cast(bf16x8, aw), bfr, o[mt]);
;                     }
;                 }
	ds_add_f32 v253, v40
	v_or_b32_e32 v40, 4, v53
	v_cmp_gt_u32_e32 vcc, 63, v40
	s_and_saveexec_b64 s[12:13], vcc
	v_mov_b32_e32 v254, 0xff
	v_bfe_u32 v252, v52, 8, 6
	v_lshl_add_u32 v252, v252, 2, v52
	v_add_u32_e32 v253, 20, v252
	v_bfi_b32 v253, v254, v253, v52
	ds_add_f32 v253, v38
	s_or_b64 exec, exec, s[12:13]
	v_exp_f32_e32 v40, v44
	v_exp_f32_e32 v41, v45
	v_exp_f32_e32 v42, v46
	v_exp_f32_e32 v43, v47
	v_cmp_lt_i32_e32 vcc, 23, v54
	s_nop 1
	v_cndmask_b32_e32 v40, 0, v40, vcc
	v_cmp_lt_i32_e32 vcc, 24, v54
	s_nop 1
	v_cndmask_b32_e32 v41, 0, v41, vcc
	v_cmp_lt_i32_e32 vcc, 25, v54
	v_add_f32_e32 v44, v40, v41
	s_nop 0
	v_cndmask_b32_e32 v42, 0, v42, vcc
	v_cmp_lt_i32_e32 vcc, 26, v54
	s_nop 1
	v_cndmask_b32_e32 v43, 0, v43, vcc
	v_add_f32_e32 v45, v42, v43
	v_add_f32_e32 v44, v44, v45
	v_mov_b32_e32 v254, 0xff
	v_bfe_u32 v252, v52, 8, 6
	v_lshl_add_u32 v252, v252, 2, v52
	v_add_u32_e32 v253, 24, v252
	v_bfi_b32 v253, v254, v253, v52
	ds_add_f32 v253, v44
	v_or_b32_e32 v44, 6, v53
	v_cmp_gt_u32_e32 vcc, 63, v44
	s_and_saveexec_b64 s[12:13], vcc
	v_mov_b32_e32 v254, 0xff
	v_bfe_u32 v252, v52, 8, 6
	v_lshl_add_u32 v252, v252, 2, v52
	v_add_u32_e32 v253, 28, v252
	v_bfi_b32 v253, v254, v253, v52
	ds_add_f32 v253, v43
	s_or_b64 exec, exec, s[12:13]
	v_add3_u32 v56, s15, v186, v170
	v_add_u32_e32 v60, 0x2000, v56
	ds_read2_b64 v[44:47], v60 offset0:128 offset1:130
	v_add_f32_e32 v61, v93, v48
	v_cvt_pk_bf16_f32 v52, v48, v32
	v_add_u32_e32 v48, 0x3000, v56
	ds_read2_b64 v[56:59], v48 offset0:160 offset1:162
	v_add_f32_e32 v32, v32, v61
	v_add_f32_e32 v32, v33, v32
	v_add_f32_e32 v32, v35, v32
	v_add_f32_e32 v32, v49, v32
	v_cvt_pk_bf16_f32 v53, v33, v35
	v_cvt_pk_bf16_f32 v54, v49, v50
	v_cvt_pk_bf16_f32 v55, v51, v34
	v_add_f32_e32 v32, v50, v32
	v_add_f32_e32 v32, v51, v32
	s_waitcnt lgkmcnt(1)
	v_mfma_f32_32x32x16_bf16 v[16:31], v[44:47], v[52:55], v[16:31]
	ds_read2_b64 v[44:47], v60 offset0:132 offset1:134
	ds_read2_b64 v[48:51], v48 offset0:164 offset1:166
	v_add_f32_e32 v32, v34, v32
	v_cvt_pk_bf16_f32 v33, v37, v38
	v_cvt_pk_bf16_f32 v34, v40, v41
	v_cvt_pk_bf16_f32 v35, v42, v43
	s_waitcnt lgkmcnt(2)
	v_mfma_f32_32x32x16_bf16 v[0:15], v[56:59], v[52:55], v[0:15]
	v_add_f32_e32 v52, v39, v32
	v_cvt_pk_bf16_f32 v32, v39, v36
	v_add_f32_e32 v36, v36, v52
	v_add_f32_e32 v36, v37, v36
	v_add_f32_e32 v36, v38, v36
	v_add_f32_e32 v36, v40, v36
	v_add_f32_e32 v36, v41, v36
	s_waitcnt lgkmcnt(1)
	v_mfma_f32_32x32x16_bf16 v[16:31], v[44:47], v[32:35], v[16:31]
	v_add_f32_e32 v36, v42, v36
	v_add_f32_e32 v93, v43, v36
	s_waitcnt lgkmcnt(0)
	v_mfma_f32_32x32x16_bf16 v[0:15], v[48:51], v[32:35], v[0:15]
; template <int BR>
; DI void attn_branch(const AttnCtx& c, unsigned long long tmask, const bf16_t* kbase, size_t kpitch, const bf16_t* vbase, size_t vpitch, f32x16 (&o)[2], float& lsum) {
;     ...
;             for (int sub = 0; sub < 2; ++sub) {
;                 const int key0 = jc * 64 + sub * 32;
;                 bool skip;
;                 if (BR <= 1) skip = key0 >= c.ncvw;
;                 else if (BR == 2) skip = key0 > c.tw + 31;
;                 else skip = (key0 + 31 < c.tw - 511) || (key0 > c.tw + 31);
;                 if (skip) continue;
;                 f32x16 s;
; #pragma unroll
;                 for (int i = 0; i < 16; ++i) s[i] = sbias;
; #pragma unroll
;                 for (int st = 0; st < 4; ++st) { const bf16x8 kf = *(const LAS bf16x8*)(Ks + (sub * 32 + c.qi) * 72 + 16 * st + 8 * c.hi); s = MFMA32(kf, c.q[st], s); }
;                 float p[16];
; #pragma unroll
;                 for (int i = 0; i < 16; ++i) p[i] = __builtin_amdgcn_exp2f(s[i]);
;                 int lim;
;                 if (BR <= 1) lim = c.ncv - 1 - key0 - 4 * c.hi; else lim = c.t - key0 - 4 * c.hi;
; #pragma unroll
;                 for (int i = 0; i < 16; ++i) { const int cst = (i & 3) + 8 * (i >> 2); bool valid = cst <= lim; if (BR == 3) valid = valid && (cst > lim - 512); p[i] = valid ? p[i] : 0.f; }
; #pragma unroll
;                 for (int i = 0; i < 16; ++i) lsum += p[i];
;                 if (BR == 0) continue;
;                 if (BR == 1) {
; #pragma unroll
;                     for (int gq = 0; gq < 4; ++gq) {
;                         const int jj = jc * 16 + sub * 8 + gq * 2 + c.hi;
;                         __hip_atomic_fetch_add(c.impw + jj, (p[4 * gq] + p[4 * gq + 1]) + (p[4 * gq + 2] + p[4 * gq + 3]), __ATOMIC_RELAXED, __HIP_MEMORY_SCOPE_WORKGROUP);
;                         if (jj + 1 < 64) __hip_atomic_fetch_add(c.impw + jj + 1, p[4 * gq + 3], __ATOMIC_RELAXED, __HIP_MEMORY_SCOPE_WORKGROUP);
;                     }
;                 }
;                 unsigned pp[8];
; #pragma unroll
;                 for (int i = 0; i < 8; ++i) pp[i] = pk2(p[2 * i], p[2 * i + 1]);
; #pragma unroll
;                 for (int f = 0; f < 2; ++f) {
;                     const u32x4 bw = {pp[4 * f], pp[4 * f + 1], pp[4 * f + 2], pp[4 * f + 3]};
;                     const bf16x8 bfr = __builtin_bit_cast(bf16x8, bw);
; #pragma unroll
.LBB0_345:
	s_or_b64 exec, exec, s[10:11]
	s_or_b32 s10, s16, 32
	v_cmp_le_i32_e32 vcc, s10, v84
	s_and_saveexec_b64 s[10:11], vcc
	s_cbranch_execz .LBB0_355
	v_add3_u32 v52, s15, v185, v128
	ds_read_b128 v[32:35], v52 offset:4608
	ds_read_b128 v[48:51], v52 offset:4640
	s_xnor_b32 s16, s16, 32
	s_waitcnt lgkmcnt(1)
	v_mfma_f32_32x32x16_bf16 v[32:47], v[32:35], v[130:133], 0
	s_waitcnt lgkmcnt(0)
	v_mfma_f32_32x32x16_bf16 v[32:47], v[48:51], v[134:137], v[32:47]
	ds_read_b128 v[48:51], v52 offset:4672
	ds_read_b128 v[54:57], v52 offset:4704
	s_waitcnt lgkmcnt(1)
	v_mfma_f32_32x32x16_bf16 v[32:47], v[48:51], v[138:141], v[32:47]
	v_sub_u32_e32 v49, s16, v91
	v_add_u32_e32 v53, v49, v73
	v_add_u32_e32 v48, s17, v78
	v_cmp_lt_i32_e32 vcc, -1, v53
	v_lshl_add_u32 v52, v48, 2, v86
	s_waitcnt lgkmcnt(0)
	v_mfma_f32_32x32x16_bf16 v[32:47], v[54:57], v[142:145], v[32:47]
	s_nop 11
	v_exp_f32_e32 v32, v32
	v_exp_f32_e32 v33, v33
	v_exp_f32_e32 v34, v34
	v_exp_f32_e32 v35, v35
	v_cndmask_b32_e32 v48, 0, v32, vcc
	v_cmp_lt_i32_e32 vcc, 0, v53
	s_nop 1
	v_cndmask_b32_e32 v32, 0, v33, vcc
	v_cmp_lt_i32_e32 vcc, 1, v53
	s_nop 1
	v_cndmask_b32_e32 v33, 0, v34, vcc
	v_cmp_lt_i32_e32 vcc, 2, v53
	v_add_f32_e32 v34, v48, v32
	s_nop 0
	v_cndmask_b32_e32 v35, 0, v35, vcc
	v_add_f32_e32 v49, v33, v35
	v_add_f32_e32 v34, v34, v49
	v_mov_b32_e32 v254, 0xff
	v_bfe_u32 v252, v52, 8, 6
	v_lshl_add_u32 v252, v252, 2, v52
	v_add_u32_e32 v253, 32, v252
	v_bfi_b32 v253, v254, v253, v52
	ds_add_f32 v253, v34
	v_or_b32_e32 v34, s17, v87
	v_cmp_gt_u32_e32 vcc, 63, v34
	s_and_saveexec_b64 s[12:13], vcc
	v_mov_b32_e32 v254, 0xff
	v_bfe_u32 v252, v52, 8, 6
	v_lshl_add_u32 v252, v252, 2, v52
	v_add_u32_e32 v253, 36, v252
	v_bfi_b32 v253, v254, v253, v52
	ds_add_f32 v253, v35
	s_or_b64 exec, exec, s[12:13]
	v_exp_f32_e32 v34, v36
	v_exp_f32_e32 v36, v37
	v_exp_f32_e32 v37, v38
	v_exp_f32_e32 v38, v39
	v_cmp_lt_i32_e32 vcc, 7, v53
	s_nop 1
	v_cndmask_b32_e32 v49, 0, v34, vcc
	v_cmp_lt_i32_e32 vcc, 8, v53
	s_nop 1
	v_cndmask_b32_e32 v50, 0, v36, vcc
	v_cmp_lt_i32_e32 vcc, 9, v53
	v_add_f32_e32 v36, v49, v50
	s_nop 0
	v_cndmask_b32_e32 v51, 0, v37, vcc
	v_cmp_lt_i32_e32 vcc, 10, v53
	s_nop 1
	v_cndmask_b32_e32 v34, 0, v38, vcc
	v_add_f32_e32 v37, v51, v34
	v_add_f32_e32 v36, v36, v37
	v_mov_b32_e32 v254, 0xff
	v_bfe_u32 v252, v52, 8, 6
	v_lshl_add_u32 v252, v252, 2, v52
	v_add_u32_e32 v253, 40, v252
	v_bfi_b32 v253, v254, v253, v52
	ds_add_f32 v253, v36
	v_or_b32_e32 v36, s17, v88
	v_cmp_gt_u32_e32 vcc, 63, v36
	s_and_saveexec_b64 s[12:13], vcc
	v_mov_b32_e32 v254, 0xff
	v_bfe_u32 v252, v52, 8, 6
	v_lshl_add_u32 v252, v252, 2, v52
	v_add_u32_e32 v253, 44, v252
	v_bfi_b32 v253, v254, v253, v52
	ds_add_f32 v253, v34
	s_or_b64 exec, exec, s[12:13]
	v_exp_f32_e32 v36, v40
	v_exp_f32_e32 v37, v41
	v_exp_f32_e32 v38, v42
	v_exp_f32_e32 v40, v43
	v_cmp_lt_i32_e32 vcc, 15, v53
	s_nop 1
	v_cndmask_b32_e32 v39, 0, v36, vcc
	v_cmp_lt_i32_e32 vcc, 16, v53
	s_nop 1
	v_cndmask_b32_e32 v36, 0, v37, vcc
	v_cmp_lt_i32_e32 vcc, 17, v53
	s_nop 1
	v_cndmask_b32_e32 v37, 0, v38, vcc
	v_cmp_lt_i32_e32 vcc, 18, v53
	s_nop 1
	v_cndmask_b32_e32 v38, 0, v40, vcc
	v_add_f32_e32 v40, v39, v36
	v_add_f32_e32 v41, v37, v38
	v_add_f32_e32 v40, v40, v41
	v_mov_b32_e32 v254, 0xff
	v_bfe_u32 v252, v52, 8, 6
	v_lshl_add_u32 v252, v252, 2, v52
	v_add_u32_e32 v253, 48, v252
	v_bfi_b32 v253, v254, v253, v52
	ds_add_f32 v253, v40
	v_or_b32_e32 v40, s17, v89
	v_cmp_gt_u32_e32 vcc, 63, v40
	s_and_saveexec_b64 s[12:13], vcc
	v_mov_b32_e32 v254, 0xff
	v_bfe_u32 v252, v52, 8, 6
	v_lshl_add_u32 v252, v252, 2, v52
	v_add_u32_e32 v253, 52, v252
	v_bfi_b32 v253, v254, v253, v52
	ds_add_f32 v253, v38
	s_or_b64 exec, exec, s[12:13]
	v_exp_f32_e32 v40, v44
	v_exp_f32_e32 v41, v45
	v_exp_f32_e32 v42, v46
	v_exp_f32_e32 v43, v47
	v_cmp_lt_i32_e32 vcc, 23, v53
	s_nop 1
	v_cndmask_b32_e32 v40, 0, v40, vcc
	v_cmp_lt_i32_e32 vcc, 24, v53
	s_nop 1
	v_cndmask_b32_e32 v41, 0, v41, vcc
	v_cmp_lt_i32_e32 vcc, 25, v53
	v_add_f32_e32 v44, v40, v41
	s_nop 0
	v_cndmask_b32_e32 v42, 0, v42, vcc
	v_cmp_lt_i32_e32 vcc, 26, v53
	s_nop 1
	v_cndmask_b32_e32 v43, 0, v43, vcc
	v_add_f32_e32 v45, v42, v43
	v_add_f32_e32 v44, v44, v45
	v_mov_b32_e32 v254, 0xff
	v_bfe_u32 v252, v52, 8, 6
	v_lshl_add_u32 v252, v252, 2, v52
	v_add_u32_e32 v253, 56, v252
	v_bfi_b32 v253, v254, v253, v52
	ds_add_f32 v253, v44
	v_or_b32_e32 v44, s17, v90
	v_cmp_gt_u32_e32 vcc, 63, v44
	s_and_saveexec_b64 s[12:13], vcc
	v_mov_b32_e32 v254, 0xff
	v_bfe_u32 v252, v52, 8, 6
	v_lshl_add_u32 v252, v252, 2, v52
	v_add_u32_e32 v253, 60, v252
	v_bfi_b32 v253, v254, v253, v52
	ds_add_f32 v253, v43
	s_or_b64 exec, exec, s[12:13]
	v_add3_u32 v56, s15, v186, v170
	v_add_u32_e32 v60, 0x2000, v56
	ds_read2_b64 v[44:47], v60 offset0:136 offset1:138
	v_add_f32_e32 v61, v93, v48
	v_cvt_pk_bf16_f32 v52, v48, v32
	v_add_u32_e32 v48, 0x3000, v56
	ds_read2_b64 v[56:59], v48 offset0:168 offset1:170
	v_add_f32_e32 v32, v32, v61
	v_add_f32_e32 v32, v33, v32
	v_add_f32_e32 v32, v35, v32
	v_add_f32_e32 v32, v49, v32
	v_cvt_pk_bf16_f32 v53, v33, v35
	v_cvt_pk_bf16_f32 v54, v49, v50
	v_cvt_pk_bf16_f32 v55, v51, v34
	v_add_f32_e32 v32, v50, v32
	v_add_f32_e32 v32, v51, v32
	s_waitcnt lgkmcnt(1)
	v_mfma_f32_32x32x16_bf16 v[16:31], v[44:47], v[52:55], v[16:31]
	ds_read2_b64 v[44:47], v60 offset0:140 offset1:142
	ds_read2_b64 v[48:51], v48 offset0:172 offset1:174
	v_add_f32_e32 v32, v34, v32
	v_cvt_pk_bf16_f32 v33, v37, v38
	v_cvt_pk_bf16_f32 v34, v40, v41
	v_cvt_pk_bf16_f32 v35, v42, v43
	s_waitcnt lgkmcnt(2)
	v_mfma_f32_32x32x16_bf16 v[0:15], v[56:59], v[52:55], v[0:15]
	v_add_f32_e32 v52, v39, v32
	v_cvt_pk_bf16_f32 v32, v39, v36
	v_add_f32_e32 v36, v36, v52
	v_add_f32_e32 v36, v37, v36
	v_add_f32_e32 v36, v38, v36
	v_add_f32_e32 v36, v40, v36
	v_add_f32_e32 v36, v41, v36
	s_waitcnt lgkmcnt(1)
	v_mfma_f32_32x32x16_bf16 v[16:31], v[44:47], v[32:35], v[16:31]
	v_add_f32_e32 v36, v42, v36
	v_add_f32_e32 v93, v43, v36
	s_waitcnt lgkmcnt(0)
	v_mfma_f32_32x32x16_bf16 v[0:15], v[48:51], v[32:35], v[0:15]

; DI void attn_item(const Args& a, int l, int item, LAS unsigned char* lds, bool dry = false) {
;     ...
;     for (int k = 0; k < 8; ++k) {
;         const int tk = wid * 8 + k;
;         float val = (imp[(0 * 64 + tk) * 64 + lane] * linv[tk] + imp[(1 * 64 + tk) * 64 + lane] * linv[64 + tk]) + (imp[(2 * 64 + tk) * 64 + lane] * linv[128 + tk] + imp[(3 * 64 + tk) * 64 + lane] * linv[192 + tk]);
;         const bool causal = lane <= qb, forced = (lane == 0) || (lane == qb) || (lane == qb - 1);
;         val = causal ? val + (forced ? 1000.f : 0.f) : -1.f;
;         int rank = 0;
; #pragma unroll
;         for (int j = 0; j < 64; ++j) { const float vj = __builtin_bit_cast(float, __builtin_amdgcn_readlane(__builtin_bit_cast(int, val), j)); rank += (vj > val || (vj == val && j < lane)) ? 1 : 0; }
.LBB0_363:
	v_add_u32_e32 v41, 0, v80
	v_mov_b32_e32 v254, 0xff
	v_bfe_u32 v39, v35, 8, 6
	v_lshl_add_u32 v39, v39, 2, v35
	v_bfi_b32 v39, v254, v39, v35
	v_add_u32_e32 v38, 0x10200, v41
	v_add_u32_e32 v40, 0x10300, v41
	ds_read2st64_b32 v[36:37], v39 offset1:64
	ds_read_b32 v38, v38
	ds_read_b32 v40, v40
	ds_read2st64_b32 v[42:43], v39 offset0:128 offset1:192
	v_add_u32_e32 v39, 0x10400, v41
	v_add_u32_e32 v41, 0x10500, v41
	ds_read_b32 v39, v39
	ds_read_b32 v41, v41
	s_waitcnt lgkmcnt(2)
	v_mov_b32_e32 v45, v42
	v_mov_b32_e32 v42, v37
	v_mov_b32_e32 v44, v36
	s_waitcnt lgkmcnt(0)
	v_pk_mul_f32 v[36:37], v[42:43], v[40:41]
	s_nop 0
	v_pk_fma_f32 v[36:37], v[44:45], v[38:39], v[36:37]
	s_nop 0
	v_pk_add_f32 v[36:37], v[36:37], v[36:37] op_sel:[0,1] op_sel_hi:[1,0]
	s_nop 0
	v_add_f32_e32 v36, v33, v36
	v_cndmask_b32_e64 v36, -1.0, v36, s[74:75]
	s_nop 0
	v_mov_b32_e32 v37, 0
	v_sub_u32_e32 v38, 63, v32
	v_mov_b32_e32 v39, v36
	v_readlane_b32 s59, v36, 0
	v_readlane_b32 s61, v36, 1
	v_readlane_b32 s63, v36, 2
	v_readlane_b32 s65, v36, 3
	s_mov_b32 s58, 63
	s_mov_b32 s60, 62
	s_mov_b32 s62, 61
	s_mov_b32 s64, 60
	v_cmp_gt_i64_e64 s[66:67], s[58:59], v[38:39]
	v_cmp_gt_i64_e64 s[68:69], s[60:61], v[38:39]
	v_cmp_gt_i64_e64 s[70:71], s[62:63], v[38:39]
	v_cmp_gt_i64_e64 s[80:81], s[64:65], v[38:39]
	v_addc_co_u32_e64 v37, s[2:3], 0, v37, s[66:67]
	v_addc_co_u32_e64 v37, s[2:3], 0, v37, s[68:69]
	v_addc_co_u32_e64 v37, s[2:3], 0, v37, s[70:71]
	v_addc_co_u32_e64 v37, s[2:3], 0, v37, s[80:81]
	v_readlane_b32 s59, v36, 4
	v_readlane_b32 s61, v36, 5
	v_readlane_b32 s63, v36, 6
	v_readlane_b32 s65, v36, 7
	s_mov_b32 s58, 59
	s_mov_b32 s60, 58
	s_mov_b32 s62, 57
	s_mov_b32 s64, 56
	v_cmp_gt_i64_e64 s[66:67], s[58:59], v[38:39]
	v_cmp_gt_i64_e64 s[68:69], s[60:61], v[38:39]
	v_cmp_gt_i64_e64 s[70:71], s[62:63], v[38:39]
	v_cmp_gt_i64_e64 s[80:81], s[64:65], v[38:39]
	v_addc_co_u32_e64 v37, s[2:3], 0, v37, s[66:67]
	v_addc_co_u32_e64 v37, s[2:3], 0, v37, s[68:69]
	v_addc_co_u32_e64 v37, s[2:3], 0, v37, s[70:71]
	v_addc_co_u32_e64 v37, s[2:3], 0, v37, s[80:81]
	v_readlane_b32 s59, v36, 8
	v_readlane_b32 s61, v36, 9
	v_readlane_b32 s63, v36, 10
	v_readlane_b32 s65, v36, 11
	s_mov_b32 s58, 55
	s_mov_b32 s60, 54
	s_mov_b32 s62, 53
	s_mov_b32 s64, 52
	v_cmp_gt_i64_e64 s[66:67], s[58:59], v[38:39]
	v_cmp_gt_i64_e64 s[68:69], s[60:61], v[38:39]
	v_cmp_gt_i64_e64 s[70:71], s[62:63], v[38:39]
	v_cmp_gt_i64_e64 s[80:81], s[64:65], v[38:39]
	v_addc_co_u32_e64 v37, s[2:3], 0, v37, s[66:67]
	v_addc_co_u32_e64 v37, s[2:3], 0, v37, s[68:69]
	v_addc_co_u32_e64 v37, s[2:3], 0, v37, s[70:71]
	v_addc_co_u32_e64 v37, s[2:3], 0, v37, s[80:81]
	v_readlane_b32 s59, v36, 12
	v_readlane_b32 s61, v36, 13
	v_readlane_b32 s63, v36, 14
	v_readlane_b32 s65, v36, 15
	s_mov_b32 s58, 51
	s_mov_b32 s60, 50
	s_mov_b32 s62, 49
	s_mov_b32 s64, 48
	v_cmp_gt_i64_e64 s[66:67], s[58:59], v[38:39]
	v_cmp_gt_i64_e64 s[68:69], s[60:61], v[38:39]
	v_cmp_gt_i64_e64 s[70:71], s[62:63], v[38:39]
	v_cmp_gt_i64_e64 s[80:81], s[64:65], v[38:39]
	v_addc_co_u32_e64 v37, s[2:3], 0, v37, s[66:67]
	v_addc_co_u32_e64 v37, s[2:3], 0, v37, s[68:69]
	v_addc_co_u32_e64 v37, s[2:3], 0, v37, s[70:71]
	v_addc_co_u32_e64 v37, s[2:3], 0, v37, s[80:81]
	v_readlane_b32 s59, v36, 16
	v_readlane_b32 s61, v36, 17
	v_readlane_b32 s63, v36, 18
	v_readlane_b32 s65, v36, 19
	s_mov_b32 s58, 47
	s_mov_b32 s60, 46
	s_mov_b32 s62, 45
	s_mov_b32 s64, 44
	v_cmp_gt_i64_e64 s[66:67], s[58:59], v[38:39]
	v_cmp_gt_i64_e64 s[68:69], s[60:61], v[38:39]
	v_cmp_gt_i64_e64 s[70:71], s[62:63], v[38:39]
	v_cmp_gt_i64_e64 s[80:81], s[64:65], v[38:39]
	v_addc_co_u32_e64 v37, s[2:3], 0, v37, s[66:67]
	v_addc_co_u32_e64 v37, s[2:3], 0, v37, s[68:69]
	v_addc_co_u32_e64 v37, s[2:3], 0, v37, s[70:71]
	v_addc_co_u32_e64 v37, s[2:3], 0, v37, s[80:81]
	v_readlane_b32 s59, v36, 20
	v_readlane_b32 s61, v36, 21
	v_readlane_b32 s63, v36, 22
	v_readlane_b32 s65, v36, 23
	s_mov_b32 s58, 43
	s_mov_b32 s60, 42
	s_mov_b32 s62, 41
	s_mov_b32 s64, 40
	v_cmp_gt_i64_e64 s[66:67], s[58:59], v[38:39]
	v_cmp_gt_i64_e64 s[68:69], s[60:61], v[38:39]
	v_cmp_gt_i64_e64 s[70:71], s[62:63], v[38:39]
	v_cmp_gt_i64_e64 s[80:81], s[64:65], v[38:39]
	v_addc_co_u32_e64 v37, s[2:3], 0, v37, s[66:67]
	v_addc_co_u32_e64 v37, s[2:3], 0, v37, s[68:69]
	v_addc_co_u32_e64 v37, s[2:3], 0, v37, s[70:71]
	v_addc_co_u32_e64 v37, s[2:3], 0, v37, s[80:81]
	v_readlane_b32 s59, v36, 24
	v_readlane_b32 s61, v36, 25
	v_readlane_b32 s63, v36, 26
	v_readlane_b32 s65, v36, 27
	s_mov_b32 s58, 39
	s_mov_b32 s60, 38
	s_mov_b32 s62, 37
	s_mov_b32 s64, 36
	v_cmp_gt_i64_e64 s[66:67], s[58:59], v[38:39]
	v_cmp_gt_i64_e64 s[68:69], s[60:61], v[38:39]
	v_cmp_gt_i64_e64 s[70:71], s[62:63], v[38:39]
	v_cmp_gt_i64_e64 s[80:81], s[64:65], v[38:39]
	v_addc_co_u32_e64 v37, s[2:3], 0, v37, s[66:67]
	v_addc_co_u32_e64 v37, s[2:3], 0, v37, s[68:69]
	v_addc_co_u32_e64 v37, s[2:3], 0, v37, s[70:71]
	v_addc_co_u32_e64 v37, s[2:3], 0, v37, s[80:81]
	v_readlane_b32 s59, v36, 28
	v_readlane_b32 s61, v36, 29
	v_readlane_b32 s63, v36, 30
	v_readlane_b32 s65, v36, 31
	s_mov_b32 s58, 35
	s_mov_b32 s60, 34
	s_mov_b32 s62, 33
	s_mov_b32 s64, 32
	v_cmp_gt_i64_e64 s[66:67], s[58:59], v[38:39]
	v_cmp_gt_i64_e64 s[68:69], s[60:61], v[38:39]
; DI void attn_item(const Args& a, int l, int item, LAS unsigned char* lds, bool dry = false) {
;     ...
;         for (int j = 0; j < 64; ++j) { const float vj = __builtin_bit_cast(float, __builtin_amdgcn_readlane(__builtin_bit_cast(int, val), j)); rank += (vj > val || (vj == val && j < lane)) ? 1 : 0; }
;         const unsigned long long mk = __ballot(rank < 16 && causal);
;         if (lane == 0) selm[tk] = mk;
	v_cmp_gt_i64_e64 s[70:71], s[62:63], v[38:39]
	v_cmp_gt_i64_e64 s[80:81], s[64:65], v[38:39]
	v_addc_co_u32_e64 v37, s[2:3], 0, v37, s[66:67]
	v_addc_co_u32_e64 v37, s[2:3], 0, v37, s[68:69]
	v_addc_co_u32_e64 v37, s[2:3], 0, v37, s[70:71]
	v_addc_co_u32_e64 v37, s[2:3], 0, v37, s[80:81]
	v_readlane_b32 s59, v36, 32
	v_readlane_b32 s61, v36, 33
	v_readlane_b32 s63, v36, 34
	v_readlane_b32 s65, v36, 35
	s_mov_b32 s58, 31
	s_mov_b32 s60, 30
	s_mov_b32 s62, 29
	s_mov_b32 s64, 28
	v_cmp_gt_i64_e64 s[66:67], s[58:59], v[38:39]
	v_cmp_gt_i64_e64 s[68:69], s[60:61], v[38:39]
	v_cmp_gt_i64_e64 s[70:71], s[62:63], v[38:39]
	v_cmp_gt_i64_e64 s[80:81], s[64:65], v[38:39]
	v_addc_co_u32_e64 v37, s[2:3], 0, v37, s[66:67]
	v_addc_co_u32_e64 v37, s[2:3], 0, v37, s[68:69]
	v_addc_co_u32_e64 v37, s[2:3], 0, v37, s[70:71]
	v_addc_co_u32_e64 v37, s[2:3], 0, v37, s[80:81]
	v_readlane_b32 s59, v36, 36
	v_readlane_b32 s61, v36, 37
	v_readlane_b32 s63, v36, 38
	v_readlane_b32 s65, v36, 39
	s_mov_b32 s58, 27
	s_mov_b32 s60, 26
	s_mov_b32 s62, 25
	s_mov_b32 s64, 24
	v_cmp_gt_i64_e64 s[66:67], s[58:59], v[38:39]
	v_cmp_gt_i64_e64 s[68:69], s[60:61], v[38:39]
	v_cmp_gt_i64_e64 s[70:71], s[62:63], v[38:39]
	v_cmp_gt_i64_e64 s[80:81], s[64:65], v[38:39]
	v_addc_co_u32_e64 v37, s[2:3], 0, v37, s[66:67]
	v_addc_co_u32_e64 v37, s[2:3], 0, v37, s[68:69]
	v_addc_co_u32_e64 v37, s[2:3], 0, v37, s[70:71]
	v_addc_co_u32_e64 v37, s[2:3], 0, v37, s[80:81]
	v_readlane_b32 s59, v36, 40
	v_readlane_b32 s61, v36, 41
	v_readlane_b32 s63, v36, 42
	v_readlane_b32 s65, v36, 43
	s_mov_b32 s58, 23
	s_mov_b32 s60, 22
	s_mov_b32 s62, 21
	s_mov_b32 s64, 20
	v_cmp_gt_i64_e64 s[66:67], s[58:59], v[38:39]
	v_cmp_gt_i64_e64 s[68:69], s[60:61], v[38:39]
	v_cmp_gt_i64_e64 s[70:71], s[62:63], v[38:39]
	v_cmp_gt_i64_e64 s[80:81], s[64:65], v[38:39]
	v_addc_co_u32_e64 v37, s[2:3], 0, v37, s[66:67]
	v_addc_co_u32_e64 v37, s[2:3], 0, v37, s[68:69]
	v_addc_co_u32_e64 v37, s[2:3], 0, v37, s[70:71]
	v_addc_co_u32_e64 v37, s[2:3], 0, v37, s[80:81]
	v_readlane_b32 s59, v36, 44
	v_readlane_b32 s61, v36, 45
	v_readlane_b32 s63, v36, 46
	v_readlane_b32 s65, v36, 47
	s_mov_b32 s58, 19
	s_mov_b32 s60, 18
	s_mov_b32 s62, 17
	s_mov_b32 s64, 16
	v_cmp_gt_i64_e64 s[66:67], s[58:59], v[38:39]
	v_cmp_gt_i64_e64 s[68:69], s[60:61], v[38:39]
	v_cmp_gt_i64_e64 s[70:71], s[62:63], v[38:39]
	v_cmp_gt_i64_e64 s[80:81], s[64:65], v[38:39]
	v_addc_co_u32_e64 v37, s[2:3], 0, v37, s[66:67]
	v_addc_co_u32_e64 v37, s[2:3], 0, v37, s[68:69]
	v_addc_co_u32_e64 v37, s[2:3], 0, v37, s[70:71]
	v_addc_co_u32_e64 v37, s[2:3], 0, v37, s[80:81]
	v_readlane_b32 s59, v36, 48
	v_readlane_b32 s61, v36, 49
	v_readlane_b32 s63, v36, 50
	v_readlane_b32 s65, v36, 51
	s_mov_b32 s58, 15
	s_mov_b32 s60, 14
	s_mov_b32 s62, 13
	s_mov_b32 s64, 12
	v_cmp_gt_i64_e64 s[66:67], s[58:59], v[38:39]
	v_cmp_gt_i64_e64 s[68:69], s[60:61], v[38:39]
	v_cmp_gt_i64_e64 s[70:71], s[62:63], v[38:39]
	v_cmp_gt_i64_e64 s[80:81], s[64:65], v[38:39]
	v_addc_co_u32_e64 v37, s[2:3], 0, v37, s[66:67]
	v_addc_co_u32_e64 v37, s[2:3], 0, v37, s[68:69]
	v_addc_co_u32_e64 v37, s[2:3], 0, v37, s[70:71]
	v_addc_co_u32_e64 v37, s[2:3], 0, v37, s[80:81]
	v_readlane_b32 s59, v36, 52
	v_readlane_b32 s61, v36, 53
	v_readlane_b32 s63, v36, 54
	v_readlane_b32 s65, v36, 55
	s_mov_b32 s58, 11
	s_mov_b32 s60, 10
	s_mov_b32 s62, 9
	s_mov_b32 s64, 8
	v_cmp_gt_i64_e64 s[66:67], s[58:59], v[38:39]
	v_cmp_gt_i64_e64 s[68:69], s[60:61], v[38:39]
	v_cmp_gt_i64_e64 s[70:71], s[62:63], v[38:39]
	v_cmp_gt_i64_e64 s[80:81], s[64:65], v[38:39]
	v_addc_co_u32_e64 v37, s[2:3], 0, v37, s[66:67]
	v_addc_co_u32_e64 v37, s[2:3], 0, v37, s[68:69]
	v_addc_co_u32_e64 v37, s[2:3], 0, v37, s[70:71]
	v_addc_co_u32_e64 v37, s[2:3], 0, v37, s[80:81]
	v_readlane_b32 s59, v36, 56
	v_readlane_b32 s61, v36, 57
	v_readlane_b32 s63, v36, 58
	v_readlane_b32 s65, v36, 59
	s_mov_b32 s58, 7
	s_mov_b32 s60, 6
	s_mov_b32 s62, 5
	s_mov_b32 s64, 4
	v_cmp_gt_i64_e64 s[66:67], s[58:59], v[38:39]
	v_cmp_gt_i64_e64 s[68:69], s[60:61], v[38:39]
	v_cmp_gt_i64_e64 s[70:71], s[62:63], v[38:39]
	v_cmp_gt_i64_e64 s[80:81], s[64:65], v[38:39]
	v_addc_co_u32_e64 v37, s[2:3], 0, v37, s[66:67]
	v_addc_co_u32_e64 v37, s[2:3], 0, v37, s[68:69]
	v_addc_co_u32_e64 v37, s[2:3], 0, v37, s[70:71]
	v_addc_co_u32_e64 v37, s[2:3], 0, v37, s[80:81]
	v_readlane_b32 s59, v36, 60
	v_readlane_b32 s61, v36, 61
	v_readlane_b32 s63, v36, 62
	v_readlane_b32 s65, v36, 63
	s_mov_b32 s58, 3
	s_mov_b32 s60, 2
	s_mov_b32 s62, 1
	s_mov_b32 s64, 0
	v_cmp_gt_i64_e64 s[66:67], s[58:59], v[38:39]
	v_cmp_gt_i64_e64 s[68:69], s[60:61], v[38:39]
	v_cmp_gt_i64_e64 s[70:71], s[62:63], v[38:39]
	v_cmp_gt_i64_e64 s[80:81], s[64:65], v[38:39]
	v_addc_co_u32_e64 v37, s[2:3], 0, v37, s[66:67]
	v_addc_co_u32_e64 v37, s[2:3], 0, v37, s[68:69]
	v_addc_co_u32_e64 v37, s[2:3], 0, v37, s[70:71]
	v_addc_co_u32_e64 v37, s[2:3], 0, v37, s[80:81]
	v_mov_b32_e32 v36, v37
	v_cmp_gt_u32_e32 vcc, 16, v36
	s_and_b64 s[2:3], s[74:75], vcc
	v_cndmask_b32_e64 v36, 0, 1, s[2:3]
	v_cmp_ne_u32_e32 vcc, 0, v36
	s_and_saveexec_b64 s[2:3], s[38:39]
	s_cbranch_execz .LBB0_362
	v_add_u32_e32 v36, 0, v34
	v_mov_b64_e32 v[38:39], vcc
	ds_write_b64 v36, v[38:39]
	s_branch .LBB0_362
